# P8 combine loop: independent load groups issued together (two of four serialized round trips per iteration removed)
# baseline (speedup 1.0000x reference)
; __global__ void __launch_bounds__(NTHR, 2) fwd_megakernel(Args a) {
;     ...
;             for (int k = 0; k < kn; ++k) { const size_t t = (size_t)gw + (size_t)(k0 + k) * NGW;
; #pragma unroll
;                 for (int hh = 0; hh < 2; ++hh) { const int sl = hh * 64 + lane; const int e = EL[k * 128 + sl]; const float hd = HW[k * 128 + sl] * USC[e] * RSTDF[t];
;                     HW[k * 128 + sl] = GATE[t * 128 + sl] * 0.5f * hd * (1.f + erff(hd * 0.70710678118654752f)) * VSC[e]; } }
.LBB0_899:
	s_add_i32 s1, s67, s72
	s_add_i32 s0, s66, s73
	s_mul_i32 s30, s85, s1
	s_mul_hi_u32 s31, s84, s1
	s_add_i32 s31, s31, s30
	s_mul_i32 s30, s84, s1
	s_mul_i32 s1, s81, s0
	s_mul_hi_u32 s35, s41, s0
	s_add_i32 s35, s35, s1
	s_mul_i32 s0, s41, s0
	s_add_u32 s0, s0, s83
	s_addc_u32 s1, s35, s87
	s_add_u32 s30, s30, s38
	s_addc_u32 s31, s31, s39
	s_lshl_b32 s35, s66, 7
	s_lshl_b32 s36, s67, 7
	s_lshl_b64 vcc, s[30:31], 2
	s_add_u32 vcc_lo, s52, vcc_lo
	s_addc_u32 vcc_hi, s53, vcc_hi
	s_lshl_b64 s[56:57], s[0:1], 2
	v_or_b32_e32 v3, s36, v64
	s_add_u32 s56, s52, s56
	v_or_b32_e32 v2, s35, v65
	v_lshl_add_u32 v26, v3, 2, s45
	s_addc_u32 s57, s53, s57
	global_load_dword v0, v67, vcc
	s_waitcnt lgkmcnt(0)
	global_load_dword v1, v67, s[56:57]
	v_lshl_add_u32 v27, v2, 2, s45
	ds_read2st64_b32 v[2:3], v26 offset1:32
	ds_read2st64_b32 v[4:5], v27 offset1:32
	s_lshl_b64 s[30:31], s[30:31], 9
	s_lshl_b64 s[0:1], s[0:1], 9
	s_add_i32 s67, s67, 2
	s_waitcnt lgkmcnt(1)
	v_mov_b32_e32 v6, v3
	v_ashrrev_i32_e32 v3, 31, v2
	s_waitcnt lgkmcnt(0)
	v_mov_b32_e32 v7, v5
	v_ashrrev_i32_e32 v5, 31, v4
	v_lshlrev_b64 v[8:9], 2, v[2:3]
	v_lshl_add_u64 v[2:3], s[60:61], 0, v[8:9]
	v_lshlrev_b64 v[10:11], 2, v[4:5]
	v_lshl_add_u64 v[4:5], s[60:61], 0, v[10:11]
	global_load_dword v2, v[2:3], off
	s_nop 0
	global_load_dword v3, v[4:5], off
	v_lshl_add_u64 v[4:5], v[78:79], 0, s[0:1]
	v_lshl_add_u64 v[8:9], s[62:63], 0, v[8:9]
	v_lshl_add_u64 v[10:11], s[62:63], 0, v[10:11]
	s_mov_b32 s0, 0xb9c68948
	s_add_i32 s66, s66, 2
	s_add_i32 s58, s58, -2
	s_cmp_lg_u32 s58, 0
	v_lshl_add_u64 v[28:29], v[78:79], 0, s[30:31]
	global_load_dword v12, v[28:29], off
	global_load_dword v13, v[4:5], off
	s_nop 0
	global_load_dword v8, v[8:9], off
	s_nop 0
	global_load_dword v9, v[10:11], off
	s_waitcnt vmcnt(4)
	v_pk_mul_f32 v[2:3], v[6:7], v[2:3]
	s_nop 0
	v_pk_mul_f32 v[6:7], v[2:3], v[0:1]
	s_nop 0
	v_pk_mul_f32 v[14:15], v[6:7], s[80:81] op_sel_hi:[1,0]
	s_waitcnt vmcnt(2)
	v_pk_mul_f32 v[12:13], v[12:13], 0.5 op_sel_hi:[1,0]
	s_nop 0
	v_pk_mul_f32 v[12:13], v[6:7], v[12:13]
	v_and_b32_e32 v17, 0x7fffffff, v15
	v_and_b32_e32 v16, 0x7fffffff, v14
	v_mov_b64_e32 v[6:7], s[0:1]
	v_pk_fma_f32 v[18:19], v[16:17], s[82:83], v[6:7] op_sel_hi:[1,0,0]
	v_cmp_lt_f32_e64 vcc, |v15|, 1.0
	v_pk_fma_f32 v[18:19], v[16:17], v[18:19], s[90:91] op_sel_hi:[1,1,0]
	v_cmp_lt_f32_e64 s[30:31], |v14|, 1.0
	v_pk_fma_f32 v[18:19], v[16:17], v[18:19], s[92:93] op_sel_hi:[1,1,0]
	s_nop 0
	v_pk_fma_f32 v[18:19], v[16:17], v[18:19], s[94:95] op_sel_hi:[1,1,0]
	s_nop 0
	v_pk_fma_f32 v[18:19], v[16:17], v[18:19], s[96:97] op_sel_hi:[1,1,0]
	s_nop 0
	v_pk_fma_f32 v[18:19], v[16:17], v[18:19], s[4:5] op_sel_hi:[1,1,0]
	s_nop 0
	v_pk_fma_f32 v[18:19], v[16:17], v[18:19], v[16:17]
	s_nop 0
	v_mul_f32_e32 v20, 0xbfb8aa3b, v19
	v_fma_f32 v21, v19, s89, -v20
	v_rndne_f32_e32 v22, v20
	v_fmac_f32_e32 v21, 0xb2a5705f, v19
	v_sub_f32_e32 v20, v20, v22
	v_add_f32_e32 v20, v20, v21
	v_exp_f32_e32 v20, v20
	v_cvt_i32_f32_e32 v21, v22
	v_cmp_nlt_f32_e64 s[0:1], s91, v19
	v_ldexp_f32 v20, v20, v21
	s_nop 0
	v_cndmask_b32_e64 v20, 0, v20, s[0:1]
	v_cmp_ngt_f32_e64 s[0:1], s93, v19
	s_nop 1
	v_cndmask_b32_e64 v19, v132, v20, s[0:1]
	v_mul_f32_e32 v20, 0xbfb8aa3b, v18
	v_fma_f32 v21, v18, s89, -v20
	v_rndne_f32_e32 v22, v20
	v_fmac_f32_e32 v21, 0xb2a5705f, v18
	v_sub_f32_e32 v20, v20, v22
	v_add_f32_e32 v20, v20, v21
	v_exp_f32_e32 v20, v20
	v_cvt_i32_f32_e32 v21, v22
	v_cmp_nlt_f32_e64 s[0:1], s91, v18
	v_ldexp_f32 v20, v20, v21
	s_nop 0
	v_cndmask_b32_e64 v20, 0, v20, s[0:1]
	v_cmp_ngt_f32_e64 s[0:1], s93, v18
	s_nop 1
	v_cndmask_b32_e64 v18, v132, v20, s[0:1]
	s_mov_b32 s0, 0x3ba10414
	v_pk_mul_f32 v[20:21], v[14:15], v[14:15]
	v_mov_b64_e32 v[22:23], s[0:1]
	v_pk_fma_f32 v[24:25], v[20:21], s[34:35], v[22:23] op_sel_hi:[1,0,0]
	v_pk_add_f32 v[18:19], v[18:19], 1.0 op_sel_hi:[1,0] neg_lo:[1,0] neg_hi:[1,0]
	v_pk_fma_f32 v[24:25], v[20:21], v[24:25], s[44:45] op_sel_hi:[1,1,0]
	s_nop 0
	v_pk_fma_f32 v[24:25], v[20:21], v[24:25], s[88:89] op_sel_hi:[1,1,0]
	s_nop 0
	v_pk_fma_f32 v[24:25], v[20:21], v[24:25], s[86:87] op_sel_hi:[1,1,0]
	s_nop 0
	v_pk_fma_f32 v[20:21], v[20:21], v[24:25], s[40:41] op_sel_hi:[1,1,0]
	s_nop 0
	v_pk_fma_f32 v[16:17], v[16:17], v[20:21], v[16:17]
	s_nop 0
	v_cndmask_b32_e64 v16, v18, v16, s[30:31]
	v_cndmask_b32_e32 v17, v19, v17, vcc
	v_bfi_b32 v15, s5, v17, v15
	v_bfi_b32 v14, s5, v16, v14
	v_pk_add_f32 v[14:15], v[14:15], 1.0 op_sel_hi:[1,0]
	s_nop 0
	v_pk_mul_f32 v[12:13], v[12:13], v[14:15]
	s_waitcnt vmcnt(0)
; __global__ void __launch_bounds__(NTHR, 2) fwd_megakernel(Args a) {
;     ...
;             for (int k = 0; k < kn; ++k) { const size_t t = (size_t)gw + (size_t)(k0 + k) * NGW;
; #pragma unroll
;                 for (int hh = 0; hh < 2; ++hh) { const int sl = hh * 64 + lane; const int e = EL[k * 128 + sl]; const float hd = HW[k * 128 + sl] * USC[e] * RSTDF[t];
;                     HW[k * 128 + sl] = GATE[t * 128 + sl] * 0.5f * hd * (1.f + erff(hd * 0.70710678118654752f)) * VSC[e]; } }
	v_pk_mul_f32 v[8:9], v[8:9], v[12:13]
	ds_write_b32 v26, v8 offset:8192
	ds_write_b32 v27, v9 offset:8192
	v_or_b32_e32 v9, s36, v76
	v_or_b32_e32 v8, s35, v77
	v_lshl_add_u32 v18, v9, 2, s45
	v_lshl_add_u32 v19, v8, 2, s45
	ds_read2st64_b32 v[8:9], v18 offset1:32
	ds_read2st64_b32 v[10:11], v19 offset1:32
	s_waitcnt lgkmcnt(1)
	v_mov_b32_e32 v12, v9
	v_ashrrev_i32_e32 v9, 31, v8
	s_waitcnt lgkmcnt(0)
	v_mov_b32_e32 v13, v11
	v_ashrrev_i32_e32 v11, 31, v10
	v_lshlrev_b64 v[8:9], 2, v[8:9]
	v_lshl_add_u64 v[14:15], s[60:61], 0, v[8:9]
	v_lshlrev_b64 v[10:11], 2, v[10:11]
	v_lshl_add_u64 v[16:17], s[60:61], 0, v[10:11]
	global_load_dword v14, v[14:15], off
	s_nop 0
	global_load_dword v15, v[16:17], off
	s_nop 0
	global_load_dword v2, v[28:29], off offset:256
	s_nop 0
	global_load_dword v3, v[4:5], off offset:256
	v_lshl_add_u64 v[30:31], s[62:63], 0, v[8:9]
	v_lshl_add_u64 v[32:33], s[62:63], 0, v[10:11]
	global_load_dword v34, v[30:31], off
	global_load_dword v35, v[32:33], off
	s_waitcnt vmcnt(4)
	v_pk_mul_f32 v[12:13], v[12:13], v[14:15]
	s_nop 0
	v_pk_mul_f32 v[0:1], v[12:13], v[0:1]
	s_waitcnt vmcnt(2)
	v_pk_mul_f32 v[2:3], v[2:3], 0.5 op_sel_hi:[1,0]
	s_nop 0
	v_pk_mul_f32 v[2:3], v[0:1], v[2:3]
	v_pk_mul_f32 v[0:1], v[0:1], s[80:81] op_sel_hi:[1,0]
	s_nop 0
	v_and_b32_e32 v5, 0x7fffffff, v1
	v_and_b32_e32 v4, 0x7fffffff, v0
	v_pk_fma_f32 v[6:7], v[4:5], s[82:83], v[6:7] op_sel_hi:[1,0,0]
	v_cmp_lt_f32_e64 vcc, |v1|, 1.0
	v_pk_fma_f32 v[6:7], v[4:5], v[6:7], s[90:91] op_sel_hi:[1,1,0]
	v_cmp_lt_f32_e64 s[0:1], |v0|, 1.0
	v_pk_fma_f32 v[6:7], v[4:5], v[6:7], s[92:93] op_sel_hi:[1,1,0]
	s_nop 0
	v_pk_fma_f32 v[6:7], v[4:5], v[6:7], s[94:95] op_sel_hi:[1,1,0]
	s_nop 0
	v_pk_fma_f32 v[6:7], v[4:5], v[6:7], s[96:97] op_sel_hi:[1,1,0]
	s_nop 0
	v_pk_fma_f32 v[6:7], v[4:5], v[6:7], s[4:5] op_sel_hi:[1,1,0]
	s_nop 0
	v_pk_fma_f32 v[6:7], v[4:5], v[6:7], v[4:5]
	s_nop 0
	v_mul_f32_e32 v12, 0xbfb8aa3b, v7
	v_fma_f32 v13, v7, s89, -v12
	v_rndne_f32_e32 v14, v12
	v_fmac_f32_e32 v13, 0xb2a5705f, v7
	v_sub_f32_e32 v12, v12, v14
	v_add_f32_e32 v12, v12, v13
	v_exp_f32_e32 v12, v12
	v_cvt_i32_f32_e32 v13, v14
	v_cmp_nlt_f32_e64 s[30:31], s91, v7
	v_ldexp_f32 v12, v12, v13
	s_nop 0
	v_cndmask_b32_e64 v12, 0, v12, s[30:31]
	v_cmp_ngt_f32_e64 s[30:31], s93, v7
	s_nop 1
	v_cndmask_b32_e64 v7, v132, v12, s[30:31]
	v_mul_f32_e32 v12, 0xbfb8aa3b, v6
	v_fma_f32 v13, v6, s89, -v12
	v_rndne_f32_e32 v14, v12
	v_fmac_f32_e32 v13, 0xb2a5705f, v6
	v_sub_f32_e32 v12, v12, v14
	v_add_f32_e32 v12, v12, v13
	v_exp_f32_e32 v12, v12
	v_cvt_i32_f32_e32 v13, v14
	v_cmp_nlt_f32_e64 s[30:31], s91, v6
	v_ldexp_f32 v12, v12, v13
	s_nop 0
	v_cndmask_b32_e64 v12, 0, v12, s[30:31]
	v_cmp_ngt_f32_e64 s[30:31], s93, v6
	s_nop 1
	v_cndmask_b32_e64 v6, v132, v12, s[30:31]
	v_pk_mul_f32 v[12:13], v[0:1], v[0:1]
	v_pk_add_f32 v[6:7], v[6:7], 1.0 op_sel_hi:[1,0] neg_lo:[1,0] neg_hi:[1,0]
	v_pk_fma_f32 v[14:15], v[12:13], s[34:35], v[22:23] op_sel_hi:[1,0,0]
	s_nop 0
	v_pk_fma_f32 v[14:15], v[12:13], v[14:15], s[44:45] op_sel_hi:[1,1,0]
	s_nop 0
	v_pk_fma_f32 v[14:15], v[12:13], v[14:15], s[88:89] op_sel_hi:[1,1,0]
	s_nop 0
	v_pk_fma_f32 v[14:15], v[12:13], v[14:15], s[86:87] op_sel_hi:[1,1,0]
	s_nop 0
	v_pk_fma_f32 v[12:13], v[12:13], v[14:15], s[40:41] op_sel_hi:[1,1,0]
	s_nop 0
	v_pk_fma_f32 v[4:5], v[4:5], v[12:13], v[4:5]
	s_nop 0
	v_cndmask_b32_e64 v4, v6, v4, s[0:1]
	v_cndmask_b32_e32 v5, v7, v5, vcc
	v_bfi_b32 v1, s5, v5, v1
	v_bfi_b32 v0, s5, v4, v0
	v_pk_add_f32 v[0:1], v[0:1], 1.0 op_sel_hi:[1,0]
	s_nop 0
	v_pk_mul_f32 v[0:1], v[2:3], v[0:1]
	s_waitcnt vmcnt(0)
	v_pk_mul_f32 v[0:1], v[34:35], v[0:1]
	ds_write_b32 v18, v0 offset:8192
	ds_write_b32 v19, v1 offset:8192
	s_cbranch_scc1 .LBB0_899
	s_and_b32 s30, s33, 30
	s_cmp_lg_u32 s33, s30
	v_readlane_b32 s72, v234, 29
	s_cselect_b64 s[0:1], -1, 0
	v_readlane_b32 s66, v234, 27
	v_readlane_b32 s73, v234, 30
	s_and_b64 vcc, exec, s[0:1]
	s_cbranch_vccnz .LBB0_902
	s_branch .LBB0_912
